# gMLP: the four spatial-bias loads issued once at the top of the item instead of one exposed load wait per 32-token block (load de-serialisation)
# speedup vs baseline: 1.0075x; 1.0075x over previous
; #define MFMA32(a, b, c) __builtin_amdgcn_mfma_f32_32x32x16_bf16((a), (b), (c), 0, 0, 0)
; __device__ __forceinline__ void phase4_gmlp(const Args& a, LAS unsigned char* lds) {
;     ...
;     for (int item = blockIdx.x; item < 256; item += gridDim.x) {
;         const int b = item >> 4, ch = item & 15;
;         const size_t tok0 = (size_t)b * 2048 + ch * 128;
;         int tid = tid0; asm volatile("" : "+v"(tid));
;         const int lane = tid & 63, r = lane & 31, h = lane >> 5;
;         __syncthreads();
;         bf16x8_t zf[2][8];
; #pragma unroll
;         for (int dt = 0; dt < 2; ++dt)
; #pragma unroll
;             for (int ks = 0; ks < 8; ++ks) zf[dt][ks] = *(const bf16x8_t*)(zvT + ((((size_t)b * 16 + ch) * 8 + g) * 64 + 32 * dt + r) * 128 + 16 * ks + 8 * h);
;         f32x16 acc[2][4];
; #pragma unroll
;         for (int tt = 0; tt < 4; ++tt) { acc[0][tt] = zero16(); acc[1][tt] = zero16();
;             __builtin_amdgcn_sched_barrier(0);
; #pragma unroll
;             for (int ks = 0; ks < 2 * tt + 2; ++ks) {
;                 const bf16x8_t wf = *(const bf16x8_t*)(Wsp + ((size_t)g * 128 + 32 * tt + r) * 128 + 16 * ks + 8 * h);
;                 acc[0][tt] = MFMA32(zf[0][ks], wf, acc[0][tt]); acc[1][tt] = MFMA32(zf[1][ks], wf, acc[1][tt]);
;             } }
;     ...
;             const float bias = sp_b[g * 128 + tl];
.LBB0_878:
	s_and_b32 s4, s22, 15
	s_ashr_i32 s12, s22, 4
	s_lshl_b32 s23, s4, 7
	s_lshl_b32 s4, s4, 3
	s_ashr_i32 s13, s12, 31
	s_add_i32 s4, s4, s0
	v_mov_b32_e32 v178, v184
	s_lshl_b64 s[24:25], s[12:13], 13
	s_lshl_b64 s[26:27], s[4:5], 6
	s_add_u32 s4, s26, s24
	v_lshrrev_b32_e32 v2, 2, v178
	v_and_b32_e32 v181, 31, v178
	s_addc_u32 s24, s27, s25
	v_and_b32_e32 v182, 8, v2
	v_or_b32_e32 v0, s4, v181
	v_mov_b32_e32 v1, s24
	v_lshlrev_b32_e32 v128, 1, v182
	v_lshl_add_u64 v[2:3], s[2:3], 0, v[128:129]
	v_lshlrev_b64 v[0:1], 8, v[0:1]
	v_lshl_add_u64 v[4:5], v[2:3], 0, v[0:1]
	v_add_co_u32_e32 v8, vcc, s1, v4
	s_waitcnt vmcnt(0) lgkmcnt(0)
	s_nop 0
	v_addc_co_u32_e32 v9, vcc, 0, v5, vcc
	s_barrier
	v_readlane_b32 s40, v254, 12
	v_readlane_b32 s41, v254, 13
	v_add_u32_e32 v250, s15, v181
	v_mov_b32_e32 v251, 0
	v_lshl_add_u64 v[250:251], v[250:251], 2, s[40:41]
	global_load_dword v242, v[250:251], off
	global_load_dword v244, v[250:251], off offset:128
	global_load_dword v246, v[250:251], off offset:256
	global_load_dword v248, v[250:251], off offset:384
	global_load_dwordx4 v[0:3], v[4:5], off
	global_load_dwordx4 v[130:133], v[4:5], off offset:32
	global_load_dwordx4 v[134:137], v[4:5], off offset:64
	global_load_dwordx4 v[138:141], v[4:5], off offset:96
	global_load_dwordx4 v[142:145], v[4:5], off offset:128
	global_load_dwordx4 v[146:149], v[4:5], off offset:160
	global_load_dwordx4 v[150:153], v[4:5], off offset:192
	global_load_dwordx4 v[154:157], v[4:5], off offset:224
	s_nop 0
	global_load_dwordx4 v[4:7], v[8:9], off
	global_load_dwordx4 v[158:161], v[8:9], off offset:32
	global_load_dwordx4 v[170:173], v[8:9], off offset:64
	global_load_dwordx4 v[174:177], v[8:9], off offset:96
	global_load_dwordx4 v[186:189], v[8:9], off offset:128
	global_load_dwordx4 v[190:193], v[8:9], off offset:160
	global_load_dwordx4 v[194:197], v[8:9], off offset:192
	global_load_dwordx4 v[198:201], v[8:9], off offset:224
	s_lshl_b64 s[12:13], s[12:13], 11
	v_and_b32_e32 v183, 63, v178
	v_lshlrev_b32_e32 v8, 8, v181
	v_mov_b32_e32 v9, v129
	v_lshl_add_u64 v[10:11], s[10:11], 0, v[128:129]
	v_lshl_add_u64 v[16:17], v[10:11], 0, v[8:9]
	global_load_dwordx4 v[8:11], v[16:17], off
	global_load_dwordx4 v[12:15], v[16:17], off offset:32
	s_waitcnt vmcnt(1)
	v_mfma_f32_32x32x16_bf16 v[112:127], v[0:3], v[8:11], 0
	v_mfma_f32_32x32x16_bf16 v[96:111], v[4:7], v[8:11], 0
	s_waitcnt vmcnt(0)
	v_mfma_f32_32x32x16_bf16 v[112:127], v[130:133], v[12:15], v[112:127]
	v_mfma_f32_32x32x16_bf16 v[96:111], v[158:161], v[12:15], v[96:111]
	v_add_co_u32_e32 v18, vcc, s1, v16
	s_nop 1
	v_addc_co_u32_e32 v19, vcc, 0, v17, vcc
	global_load_dwordx4 v[8:11], v[18:19], off
	global_load_dwordx4 v[12:15], v[18:19], off offset:32
	s_waitcnt vmcnt(1)
	v_mfma_f32_32x32x16_bf16 v[80:95], v[0:3], v[8:11], 0
	v_mfma_f32_32x32x16_bf16 v[64:79], v[4:7], v[8:11], 0
	global_load_dwordx4 v[8:11], v[18:19], off offset:64
	s_waitcnt vmcnt(1)
	v_mfma_f32_32x32x16_bf16 v[80:95], v[130:133], v[12:15], v[80:95]
	v_mfma_f32_32x32x16_bf16 v[64:79], v[158:161], v[12:15], v[64:79]
	global_load_dwordx4 v[12:15], v[18:19], off offset:96
	s_waitcnt vmcnt(1)
	v_mfma_f32_32x32x16_bf16 v[80:95], v[134:137], v[8:11], v[80:95]
	v_mfma_f32_32x32x16_bf16 v[64:79], v[170:173], v[8:11], v[64:79]
	s_waitcnt vmcnt(0)
	v_mfma_f32_32x32x16_bf16 v[80:95], v[138:141], v[12:15], v[80:95]
	v_mfma_f32_32x32x16_bf16 v[64:79], v[174:177], v[12:15], v[64:79]
	v_add_co_u32_e32 v18, vcc, s16, v16
	s_nop 1
	v_addc_co_u32_e32 v19, vcc, 0, v17, vcc
	global_load_dwordx4 v[8:11], v[18:19], off
	global_load_dwordx4 v[12:15], v[18:19], off offset:32
	s_waitcnt vmcnt(1)
	v_mfma_f32_32x32x16_bf16 v[48:63], v[0:3], v[8:11], 0
	v_mfma_f32_32x32x16_bf16 v[32:47], v[4:7], v[8:11], 0
	global_load_dwordx4 v[8:11], v[18:19], off offset:64
	s_waitcnt vmcnt(1)
	v_mfma_f32_32x32x16_bf16 v[48:63], v[130:133], v[12:15], v[48:63]
	v_mfma_f32_32x32x16_bf16 v[32:47], v[158:161], v[12:15], v[32:47]
	global_load_dwordx4 v[12:15], v[18:19], off offset:96
	s_waitcnt vmcnt(1)
	v_mfma_f32_32x32x16_bf16 v[48:63], v[134:137], v[8:11], v[48:63]
	v_mfma_f32_32x32x16_bf16 v[32:47], v[170:173], v[8:11], v[32:47]
	global_load_dwordx4 v[8:11], v[18:19], off offset:128
	s_waitcnt vmcnt(1)
	v_mfma_f32_32x32x16_bf16 v[48:63], v[138:141], v[12:15], v[48:63]
	v_mfma_f32_32x32x16_bf16 v[32:47], v[174:177], v[12:15], v[32:47]
	global_load_dwordx4 v[12:15], v[18:19], off offset:160
	s_waitcnt vmcnt(1)
	v_mfma_f32_32x32x16_bf16 v[48:63], v[142:145], v[8:11], v[48:63]
	v_mfma_f32_32x32x16_bf16 v[32:47], v[186:189], v[8:11], v[32:47]
	s_waitcnt vmcnt(0)
	v_mfma_f32_32x32x16_bf16 v[48:63], v[146:149], v[12:15], v[48:63]
	v_mfma_f32_32x32x16_bf16 v[32:47], v[190:193], v[12:15], v[32:47]
	v_add_co_u32_e32 v162, vcc, s17, v16
	s_or_b32 s4, s12, s23
	s_nop 0
	v_addc_co_u32_e32 v163, vcc, 0, v17, vcc
	global_load_dwordx4 v[8:11], v[162:163], off
	global_load_dwordx4 v[202:205], v[162:163], off offset:32
	s_waitcnt vmcnt(1)
	v_mfma_f32_32x32x16_bf16 v[16:31], v[0:3], v[8:11], 0
	s_waitcnt vmcnt(0)
	v_mfma_f32_32x32x16_bf16 v[16:31], v[130:133], v[202:205], v[16:31]
	global_load_dwordx4 v[130:133], v[162:163], off offset:64
	v_mfma_f32_32x32x16_bf16 v[0:15], v[4:7], v[8:11], 0
	v_mfma_f32_32x32x16_bf16 v[0:15], v[158:161], v[202:205], v[0:15]
	global_load_dwordx4 v[158:161], v[162:163], off offset:96
	s_waitcnt vmcnt(1)
	v_mfma_f32_32x32x16_bf16 v[16:31], v[134:137], v[130:133], v[16:31]
	global_load_dwordx4 v[134:137], v[162:163], off offset:160
	v_mfma_f32_32x32x16_bf16 v[0:15], v[170:173], v[130:133], v[0:15]
	global_load_dwordx4 v[130:133], v[162:163], off offset:128
	s_waitcnt vmcnt(2)
; #define LAS __attribute__((address_space(3)))
; #define MFMA32(a, b, c) __builtin_amdgcn_mfma_f32_32x32x16_bf16((a), (b), (c), 0, 0, 0)
; __device__ __forceinline__ void phase4_gmlp(const Args& a, LAS unsigned char* lds) {
;     ...
;             for (int ks = 0; ks < 2 * tt + 2; ++ks) {
;                 const bf16x8_t wf = *(const bf16x8_t*)(Wsp + ((size_t)g * 128 + 32 * tt + r) * 128 + 16 * ks + 8 * h);
;                 acc[0][tt] = MFMA32(zf[0][ks], wf, acc[0][tt]); acc[1][tt] = MFMA32(zf[1][ks], wf, acc[1][tt]);
;             } }
;         __builtin_amdgcn_sched_barrier(0);
; #pragma unroll
;         for (int hb = 0; hb < 2; ++hb) {
;             u32x4 zr[8];
; #pragma unroll
;             for (int it = 0; it < 8; ++it) zr[it] = __builtin_nontemporal_load((const u32x4*)(zu + (tok0 + (lane >> 3) + 8 * (8 * hb + it)) * 512 + g * 64 + (lane & 7) * 8));
; #pragma unroll
;             for (int it = 0; it < 8; ++it) { LAS unsigned char* p = tile + ((lane >> 3) + 8 * (8 * hb + it)) * G_TSTR + (lane & 7) * 16;
;                 *(LAS u32x2*)p = (u32x2){zr[it].x, zr[it].y}; *(LAS u32x2*)(p + 8) = (u32x2){zr[it].z, zr[it].w}; }
	v_mfma_f32_32x32x16_bf16 v[16:31], v[138:141], v[158:161], v[16:31]
	v_mfma_f32_32x32x16_bf16 v[0:15], v[174:177], v[158:161], v[0:15]
	s_waitcnt vmcnt(0)
	v_mfma_f32_32x32x16_bf16 v[16:31], v[142:145], v[130:133], v[16:31]
	v_mfma_f32_32x32x16_bf16 v[0:15], v[186:189], v[130:133], v[0:15]
	global_load_dwordx4 v[130:133], v[162:163], off offset:192
	v_mfma_f32_32x32x16_bf16 v[16:31], v[146:149], v[134:137], v[16:31]
	v_mfma_f32_32x32x16_bf16 v[0:15], v[190:193], v[134:137], v[0:15]
	global_load_dwordx4 v[134:137], v[162:163], off offset:224
	s_waitcnt vmcnt(1)
	v_mfma_f32_32x32x16_bf16 v[16:31], v[150:153], v[130:133], v[16:31]
	v_mfma_f32_32x32x16_bf16 v[0:15], v[194:197], v[130:133], v[0:15]
	s_waitcnt vmcnt(0)
	v_mfma_f32_32x32x16_bf16 v[16:31], v[154:157], v[134:137], v[16:31]
	v_mfma_f32_32x32x16_bf16 v[0:15], v[198:201], v[134:137], v[0:15]
	v_bfe_u32 v179, v178, 3, 3
	v_lshlrev_b32_e32 v128, 4, v178
	v_or_b32_e32 v160, s4, v179
	v_and_b32_e32 v128, 0x70, v128
	v_mov_b32_e32 v161, s13
	v_or_b32_e32 v158, 8, v160
	v_mov_b32_e32 v159, s13
	v_lshl_add_u64 v[162:163], s[8:9], 0, v[128:129]
	v_lshlrev_b64 v[130:131], 10, v[160:161]
	v_lshlrev_b64 v[132:133], 10, v[158:159]
	v_lshl_add_u64 v[130:131], v[162:163], 0, v[130:131]
	v_lshl_add_u64 v[132:133], v[162:163], 0, v[132:133]
	v_or_b32_e32 v154, 16, v160
	v_mov_b32_e32 v155, s13
	v_or_b32_e32 v148, 24, v160
	v_mov_b32_e32 v149, s13
	global_load_dwordx4 v[170:173], v[130:131], off nt
	global_load_dwordx4 v[174:177], v[132:133], off nt
	v_lshlrev_b64 v[130:131], 10, v[154:155]
	v_lshlrev_b64 v[132:133], 10, v[148:149]
	v_lshl_add_u64 v[130:131], v[162:163], 0, v[130:131]
	v_lshl_add_u64 v[132:133], v[162:163], 0, v[132:133]
	v_or_b32_e32 v142, 32, v160
	v_mov_b32_e32 v143, s13
	v_or_b32_e32 v136, 40, v160
	v_mov_b32_e32 v137, s13
	global_load_dwordx4 v[186:189], v[130:131], off nt
	global_load_dwordx4 v[190:193], v[132:133], off nt
	v_lshlrev_b64 v[130:131], 10, v[142:143]
	v_lshlrev_b64 v[132:133], 10, v[136:137]
	v_lshl_add_u64 v[130:131], v[162:163], 0, v[130:131]
	v_lshl_add_u64 v[132:133], v[162:163], 0, v[132:133]
	global_load_dwordx4 v[194:197], v[130:131], off nt
	global_load_dwordx4 v[198:201], v[132:133], off nt
	v_or_b32_e32 v132, 48, v160
	v_mov_b32_e32 v133, s13
	v_lshlrev_b64 v[130:131], 10, v[132:133]
	v_lshl_add_u64 v[134:135], v[162:163], 0, v[130:131]
	v_or_b32_e32 v130, 56, v160
	v_mov_b32_e32 v131, s13
	v_lshlrev_b64 v[138:139], 10, v[130:131]
	v_lshl_add_u64 v[138:139], v[162:163], 0, v[138:139]
	v_or_b32_e32 v156, 64, v160
	v_mov_b32_e32 v157, s13
	v_or_b32_e32 v152, 0x48, v160
	v_mov_b32_e32 v153, s13
	global_load_dwordx4 v[202:205], v[134:135], off nt
	global_load_dwordx4 v[206:209], v[138:139], off nt
	v_lshlrev_b64 v[134:135], 10, v[156:157]
	v_lshlrev_b64 v[138:139], 10, v[152:153]
	v_lshl_add_u64 v[134:135], v[162:163], 0, v[134:135]
	v_lshl_add_u64 v[138:139], v[162:163], 0, v[138:139]
	v_or_b32_e32 v150, 0x50, v160
	v_mov_b32_e32 v151, s13
	v_or_b32_e32 v146, 0x58, v160
	v_mov_b32_e32 v147, s13
	global_load_dwordx4 v[210:213], v[134:135], off nt
	global_load_dwordx4 v[214:217], v[138:139], off nt
	v_lshlrev_b64 v[134:135], 10, v[150:151]
	v_lshlrev_b64 v[138:139], 10, v[146:147]
	v_lshl_add_u64 v[134:135], v[162:163], 0, v[134:135]
	v_lshl_add_u64 v[138:139], v[162:163], 0, v[138:139]
	v_or_b32_e32 v144, 0x60, v160
	v_mov_b32_e32 v145, s13
	v_or_b32_e32 v140, 0x68, v160
	v_mov_b32_e32 v141, s13
	global_load_dwordx4 v[218:221], v[134:135], off nt
	global_load_dwordx4 v[222:225], v[138:139], off nt
	v_lshlrev_b64 v[134:135], 10, v[144:145]
	v_lshlrev_b64 v[138:139], 10, v[140:141]
	v_lshl_add_u64 v[134:135], v[162:163], 0, v[134:135]
	v_lshl_add_u64 v[138:139], v[162:163], 0, v[138:139]
	global_load_dwordx4 v[226:229], v[134:135], off nt
	global_load_dwordx4 v[230:233], v[138:139], off nt
	v_or_b32_e32 v138, 0x70, v160
	v_mov_b32_e32 v139, s13
	v_lshlrev_b64 v[134:135], 10, v[138:139]
	v_lshl_add_u64 v[134:135], v[162:163], 0, v[134:135]
	global_load_dwordx4 v[234:237], v[134:135], off nt
	v_or_b32_e32 v134, 0x78, v160
	v_mov_b32_e32 v135, s13
	v_lshlrev_b64 v[238:239], 10, v[134:135]
	v_lshl_add_u64 v[162:163], v[162:163], 0, v[238:239]
	global_load_dwordx4 v[238:241], v[162:163], off nt
	v_add_u32_e32 v180, s14, v128
	v_mad_u32_u24 v162, v179, s18, v180
	v_add_u32_e32 v163, 0x880, v162
	v_readlane_b32 s36, v254, 8
	v_readlane_b32 s40, v254, 12
	v_readlane_b32 s41, v254, 13
	v_add_u32_e32 v185, s14, v182
	s_waitcnt vmcnt(15)
	ds_write2_b64 v162, v[170:171], v[172:173] offset1:1
	s_waitcnt vmcnt(14)
	ds_write2_b64 v162, v[174:175], v[176:177] offset0:136 offset1:137
	v_cmp_lt_i32_e32 vcc, v167, v168
	v_readlane_b32 s37, v254, 9
	v_readlane_b32 s38, v254, 10
	v_cndmask_b32_e32 v182, v166, v167, vcc
	v_lshlrev_b32_e32 v182, 2, v182
	v_cmp_gt_u32_e32 vcc, 32, v183
	v_readlane_b32 s39, v254, 11
	s_waitcnt vmcnt(13)
	ds_write2_b64 v163, v[186:187], v[188:189] offset1:1
	v_add_u32_e32 v163, 0xcc0, v162
	v_add_u32_e32 v162, 0x1100, v162
	s_waitcnt vmcnt(12)
	ds_write2_b64 v163, v[190:191], v[192:193] offset1:1
	v_mov_b32_e32 v163, v129
	s_waitcnt vmcnt(11)
	ds_write2_b64 v162, v[194:195], v[196:197] offset1:1
	v_mad_u32_u24 v162, v179, s18, v164
	v_add_u32_e32 v177, v180, v162
	v_mad_u32_u24 v162, v179, s18, v165
	v_add_u32_e32 v173, v180, v162
	v_add_u32_e32 v176, 0x880, v177
	v_add_u32_e32 v175, 0xcc0, v177
	v_add_u32_e32 v174, 0x1100, v177
	v_add_u32_e32 v172, 0x880, v173
	v_add_u32_e32 v171, 0xcc0, v173
	v_add_u32_e32 v170, 0x1100, v173
	v_add_u32_e32 v178, 0x1540, v173
	s_waitcnt vmcnt(10)
	ds_write2_b64 v177, v[198:199], v[200:201] offset1:1
	s_waitcnt vmcnt(9)
; #define LAS __attribute__((address_space(3)))
; __device__ __forceinline__ void phase4_gmlp(const Args& a, LAS unsigned char* lds) {
;     ...
;         asm volatile("s_waitcnt lgkmcnt(0)" ::: "memory");
; #pragma unroll
;         for (int tt = 0; tt < 4; ++tt) {
;             const int tl = 32 * tt + r;
;             const float bias = sp_b[g * 128 + tl];
;             float ss = 0.f;
; #pragma unroll
;             for (int dt = 0; dt < 2; ++dt)
; #pragma unroll
;                 for (int ap = 0; ap < 4; ++ap) {
;                     const u32x2 zz = *(const LAS u32x2*)(tile + tl * G_TSTR + (32 * dt + 8 * ap + 4 * h) * 2);
;                     const float z0 = __uint_as_float(zz.x << 16), z1 = __uint_as_float(zz.x & 0xffff0000u), z2 = __uint_as_float(zz.y << 16), z3 = __uint_as_float(zz.y & 0xffff0000u);
;                     float v0 = z0 * (acc[dt][tt][4 * ap] + bias), v1 = z1 * (acc[dt][tt][4 * ap + 1] + bias), v2 = z2 * (acc[dt][tt][4 * ap + 2] + bias), v3 = z3 * (acc[dt][tt][4 * ap + 3] + bias);
;                     acc[dt][tt][4 * ap] = v0; acc[dt][tt][4 * ap + 1] = v1; acc[dt][tt][4 * ap + 2] = v2; acc[dt][tt][4 * ap + 3] = v3;
;                     ss += (v0 * v0 + v1 * v1) + (v2 * v2 + v3 * v3);
;                 }
;             ss += __shfl_xor(ss, 32);
;             if (h == 0) SSQ2[g * 128 + tl] = ss;
	ds_write2_b64 v177, v[202:203], v[204:205] offset0:136 offset1:137
	s_waitcnt vmcnt(8)
	ds_write2_b64 v176, v[206:207], v[208:209] offset1:1
	v_or_b32_e32 v162, s15, v181
	v_lshl_add_u64 v[186:187], v[162:163], 2, s[40:41]
	v_mad_u32_u24 v163, v181, s18, v185
	v_readlane_b32 s42, v254, 14
	v_readlane_b32 s43, v254, 15
	v_readlane_b32 s44, v254, 16
	v_readlane_b32 s45, v254, 17
	s_waitcnt vmcnt(7)
	ds_write2_b64 v175, v[210:211], v[212:213] offset1:1
	s_waitcnt vmcnt(6)
	ds_write2_b64 v174, v[214:215], v[216:217] offset1:1
	s_waitcnt vmcnt(5)
	ds_write2_b64 v173, v[218:219], v[220:221] offset1:1
	s_waitcnt vmcnt(4)
	ds_write2_b64 v173, v[222:223], v[224:225] offset0:136 offset1:137
	v_readlane_b32 s46, v254, 18
	v_readlane_b32 s47, v254, 19
	v_readlane_b32 s48, v254, 20
	s_waitcnt vmcnt(3)
	ds_write2_b64 v172, v[226:227], v[228:229] offset1:1
	s_waitcnt vmcnt(2)
	ds_write2_b64 v171, v[230:231], v[232:233] offset1:1
	v_readlane_b32 s49, v254, 21
	v_readlane_b32 s50, v254, 22
	v_readlane_b32 s51, v254, 23
	s_waitcnt vmcnt(1)
	ds_write2_b64 v170, v[234:235], v[236:237] offset1:1
	s_waitcnt vmcnt(0)
	ds_write2_b64 v178, v[238:239], v[240:241] offset1:1
	s_waitcnt lgkmcnt(0)
	ds_read2_b64 v[186:189], v163 offset1:2
	ds_read2_b64 v[190:193], v163 offset0:4 offset1:6
	ds_read2_b64 v[194:197], v163 offset0:8 offset1:10
	s_waitcnt lgkmcnt(2)
	v_lshlrev_b32_e32 v200, 16, v186
	v_and_b32_e32 v201, 0xffff0000, v186
	v_lshlrev_b32_e32 v186, 16, v187
	v_and_b32_e32 v187, 0xffff0000, v187
	v_lshlrev_b32_e32 v202, 16, v188
	v_and_b32_e32 v203, 0xffff0000, v188
	v_lshlrev_b32_e32 v188, 16, v189
	v_and_b32_e32 v189, 0xffff0000, v189
	s_waitcnt lgkmcnt(1)
	v_lshlrev_b32_e32 v204, 16, v190
	v_and_b32_e32 v205, 0xffff0000, v190
	v_lshlrev_b32_e32 v190, 16, v191
	v_and_b32_e32 v191, 0xffff0000, v191
	v_lshlrev_b32_e32 v206, 16, v192
	v_and_b32_e32 v207, 0xffff0000, v192
	v_lshlrev_b32_e32 v192, 16, v193
	v_and_b32_e32 v193, 0xffff0000, v193
	s_waitcnt lgkmcnt(0)
	v_lshlrev_b32_e32 v208, 16, v194
	v_and_b32_e32 v209, 0xffff0000, v194
	s_waitcnt vmcnt(0)
	v_pk_add_f32 v[114:115], v[114:115], v[242:243] op_sel_hi:[1,0]
	v_pk_add_f32 v[214:215], v[124:125], v[242:243] op_sel_hi:[1,0]
	v_pk_mul_f32 v[124:125], v[114:115], v[186:187]
	v_lshlrev_b32_e32 v186, 16, v195
	v_and_b32_e32 v187, 0xffff0000, v195
	v_pk_add_f32 v[98:99], v[98:99], v[242:243] op_sel_hi:[1,0]
	v_pk_add_f32 v[100:101], v[100:101], v[242:243] op_sel_hi:[1,0]
	v_pk_mul_f32 v[98:99], v[98:99], v[186:187]
	v_lshlrev_b32_e32 v186, 16, v196
	v_and_b32_e32 v187, 0xffff0000, v196
	v_lshlrev_b32_e32 v196, 16, v197
	v_and_b32_e32 v197, 0xffff0000, v197
	v_pk_add_f32 v[102:103], v[102:103], v[242:243] op_sel_hi:[1,0]
	v_pk_add_f32 v[116:117], v[116:117], v[242:243] op_sel_hi:[1,0]
	v_pk_add_f32 v[118:119], v[118:119], v[242:243] op_sel_hi:[1,0]
	v_pk_add_f32 v[210:211], v[120:121], v[242:243] op_sel_hi:[1,0]
	v_pk_add_f32 v[212:213], v[122:123], v[242:243] op_sel_hi:[1,0]
	v_pk_mul_f32 v[100:101], v[100:101], v[186:187]
	v_pk_mul_f32 v[102:103], v[102:103], v[196:197]
	v_pk_add_f32 v[112:113], v[112:113], v[242:243] op_sel_hi:[1,0]
	v_pk_mul_f32 v[122:123], v[116:117], v[202:203]
	v_pk_mul_f32 v[120:121], v[118:119], v[188:189]
	v_pk_mul_f32 v[118:119], v[210:211], v[204:205]
	v_pk_mul_f32 v[116:117], v[212:213], v[190:191]
	v_pk_mul_f32 v[114:115], v[214:215], v[206:207]
	v_pk_mul_f32 v[196:197], v[100:101], v[100:101]
	v_pk_mul_f32 v[214:215], v[102:103], v[102:103]
	v_pk_add_f32 v[216:217], v[126:127], v[242:243] op_sel_hi:[1,0]
	v_pk_mul_f32 v[126:127], v[112:113], v[200:201]
	v_pk_mul_f32 v[204:205], v[118:119], v[118:119]
	v_pk_mul_f32 v[206:207], v[116:117], v[116:117]
	ds_read2_b64 v[186:189], v163 offset0:12 offset1:14
	v_add_f32_e32 v163, v214, v215
	v_add_f32_e32 v196, v196, v197
	v_pk_mul_f32 v[112:113], v[216:217], v[192:193]
	v_pk_mul_f32 v[190:191], v[126:127], v[126:127]
	v_pk_mul_f32 v[192:193], v[124:125], v[124:125]
	v_pk_mul_f32 v[200:201], v[122:123], v[122:123]
	v_pk_mul_f32 v[202:203], v[120:121], v[120:121]
	v_add_f32_e32 v163, v196, v163
	v_add_f32_e32 v196, v206, v207
	v_add_f32_e32 v197, v204, v205
	v_add_f32_e32 v196, v197, v196
	v_add_f32_e32 v197, v202, v203
	v_add_f32_e32 v200, v200, v201
	v_add_f32_e32 v192, v192, v193
	v_add_f32_e32 v190, v190, v191
	v_pk_mul_f32 v[210:211], v[114:115], v[114:115]
	v_pk_mul_f32 v[212:213], v[112:113], v[112:113]
	v_pk_add_f32 v[96:97], v[96:97], v[242:243] op_sel_hi:[1,0]
	v_add_f32_e32 v197, v200, v197
	v_add_f32_e32 v190, v190, v192
	v_pk_mul_f32 v[96:97], v[96:97], v[208:209]
	v_add_f32_e32 v190, v190, v197
	v_add_f32_e32 v191, v212, v213
	v_add_f32_e32 v192, v210, v211
	v_pk_mul_f32 v[194:195], v[96:97], v[96:97]
	v_pk_mul_f32 v[208:209], v[98:99], v[98:99]
	v_add_f32_e32 v190, v190, v196
	v_add_f32_e32 v191, v192, v191
	s_waitcnt lgkmcnt(0)
	v_lshlrev_b32_e32 v216, 16, v186
	v_and_b32_e32 v217, 0xffff0000, v186
	v_pk_add_f32 v[104:105], v[104:105], v[242:243] op_sel_hi:[1,0]
	v_lshlrev_b32_e32 v186, 16, v187
	v_and_b32_e32 v187, 0xffff0000, v187
	v_pk_add_f32 v[106:107], v[106:107], v[242:243] op_sel_hi:[1,0]
	v_add_f32_e32 v190, v190, v191
	v_add_f32_e32 v191, v208, v209
	v_add_f32_e32 v192, v194, v195
	v_pk_mul_f32 v[104:105], v[104:105], v[216:217]
	v_pk_mul_f32 v[106:107], v[106:107], v[186:187]
	v_add_f32_e32 v191, v192, v191
	v_pk_mul_f32 v[186:187], v[104:105], v[104:105]
	v_pk_mul_f32 v[216:217], v[106:107], v[106:107]
	v_lshlrev_b32_e32 v218, 16, v188
	v_and_b32_e32 v219, 0xffff0000, v188
	v_pk_add_f32 v[108:109], v[108:109], v[242:243] op_sel_hi:[1,0]
	v_lshlrev_b32_e32 v188, 16, v189
	v_and_b32_e32 v189, 0xffff0000, v189
	v_pk_add_f32 v[110:111], v[110:111], v[242:243] op_sel_hi:[1,0]
	v_add_f32_e32 v190, v190, v191
	v_pk_mul_f32 v[108:109], v[108:109], v[218:219]
	v_pk_mul_f32 v[110:111], v[110:111], v[188:189]
	v_add_f32_e32 v163, v190, v163
	v_add_f32_e32 v190, v216, v217
	v_add_f32_e32 v186, v186, v187
	v_pk_mul_f32 v[188:189], v[108:109], v[108:109]
	v_pk_mul_f32 v[198:199], v[110:111], v[110:111]
	v_add_f32_e32 v186, v186, v190
	v_add_f32_e32 v163, v163, v186
	v_add_f32_e32 v186, v198, v199
	v_add_f32_e32 v187, v188, v189
	v_add_f32_e32 v186, v187, v186
	v_add_f32_e32 v163, v163, v186
	ds_bpermute_b32 v186, v182, v163
	s_and_saveexec_b64 s[12:13], vcc
	s_cbranch_execz .LBB0_880
	v_lshl_add_u32 v162, v162, 2, 0
	s_waitcnt lgkmcnt(0)
	v_add_f32_e32 v163, v163, v186
	v_add_u32_e32 v162, 0x22000, v162
	ds_write_b32 v162, v163
; #define LAS __attribute__((address_space(3)))
; __device__ __forceinline__ void phase4_gmlp(const Args& a, LAS unsigned char* lds) {
;     ...
;         for (int tt = 0; tt < 4; ++tt) {
;             const int tl = 32 * tt + r;
;             const float bias = sp_b[g * 128 + tl];
;             float ss = 0.f;
; #pragma unroll
;             for (int dt = 0; dt < 2; ++dt)
; #pragma unroll
;                 for (int ap = 0; ap < 4; ++ap) {
;                     const u32x2 zz = *(const LAS u32x2*)(tile + tl * G_TSTR + (32 * dt + 8 * ap + 4 * h) * 2);
;                     const float z0 = __uint_as_float(zz.x << 16), z1 = __uint_as_float(zz.x & 0xffff0000u), z2 = __uint_as_float(zz.y << 16), z3 = __uint_as_float(zz.y & 0xffff0000u);
;                     float v0 = z0 * (acc[dt][tt][4 * ap] + bias), v1 = z1 * (acc[dt][tt][4 * ap + 1] + bias), v2 = z2 * (acc[dt][tt][4 * ap + 2] + bias), v3 = z3 * (acc[dt][tt][4 * ap + 3] + bias);
;                     acc[dt][tt][4 * ap] = v0; acc[dt][tt][4 * ap + 1] = v1; acc[dt][tt][4 * ap + 2] = v2; acc[dt][tt][4 * ap + 3] = v3;
;                     ss += (v0 * v0 + v1 * v1) + (v2 * v2 + v3 * v3);
;                 }
;             ss += __shfl_xor(ss, 32);
;             if (h == 0) SSQ2[g * 128 + tl] = ss;
.LBB0_880:
	s_or_b64 exec, exec, s[12:13]
	v_readlane_b32 s36, v254, 8
	v_add_u32_e32 v162, s15, v181
	v_mov_b32_e32 v163, v129
	v_readlane_b32 s40, v254, 12
	v_readlane_b32 s41, v254, 13
	v_mul_u32_u24_e32 v183, 0x88, v181
	v_add_u32_e32 v185, v183, v185
	v_lshl_add_u64 v[162:163], v[162:163], 2, s[40:41]
	v_add_u32_e32 v183, 0x1000, v185
	s_waitcnt lgkmcnt(0)
	ds_read2_b64 v[186:189], v183 offset0:32 offset1:34
	ds_read2_b64 v[190:193], v183 offset0:36 offset1:38
	ds_read2_b64 v[194:197], v183 offset0:40 offset1:42
	ds_read2_b64 v[198:201], v183 offset0:44 offset1:46
	v_readlane_b32 s37, v254, 9
	s_waitcnt lgkmcnt(3)
	v_lshlrev_b32_e32 v204, 16, v186
	v_and_b32_e32 v205, 0xffff0000, v186
	v_lshlrev_b32_e32 v186, 16, v187
	v_and_b32_e32 v187, 0xffff0000, v187
	v_lshlrev_b32_e32 v206, 16, v188
	v_and_b32_e32 v207, 0xffff0000, v188
	v_lshlrev_b32_e32 v188, 16, v189
	v_and_b32_e32 v189, 0xffff0000, v189
	s_waitcnt lgkmcnt(2)
	v_lshlrev_b32_e32 v208, 16, v190
	v_and_b32_e32 v209, 0xffff0000, v190
	v_lshlrev_b32_e32 v190, 16, v191
	v_and_b32_e32 v191, 0xffff0000, v191
	v_lshlrev_b32_e32 v210, 16, v192
	v_and_b32_e32 v211, 0xffff0000, v192
	v_lshlrev_b32_e32 v192, 16, v193
	v_and_b32_e32 v193, 0xffff0000, v193
	s_waitcnt lgkmcnt(1)
	v_lshlrev_b32_e32 v212, 16, v194
	v_and_b32_e32 v213, 0xffff0000, v194
	v_lshlrev_b32_e32 v194, 16, v195
	v_and_b32_e32 v195, 0xffff0000, v195
	v_lshlrev_b32_e32 v214, 16, v196
	v_and_b32_e32 v215, 0xffff0000, v196
	v_lshlrev_b32_e32 v196, 16, v197
	v_and_b32_e32 v197, 0xffff0000, v197
	s_waitcnt lgkmcnt(0)
	v_lshlrev_b32_e32 v216, 16, v198
	v_and_b32_e32 v217, 0xffff0000, v198
	v_lshlrev_b32_e32 v198, 16, v199
	v_and_b32_e32 v199, 0xffff0000, v199
	v_lshlrev_b32_e32 v218, 16, v200
	v_and_b32_e32 v219, 0xffff0000, v200
	v_lshlrev_b32_e32 v200, 16, v201
	v_and_b32_e32 v201, 0xffff0000, v201
	v_readlane_b32 s38, v254, 10
	v_readlane_b32 s39, v254, 11
	v_readlane_b32 s42, v254, 14
	v_readlane_b32 s43, v254, 15
	v_readlane_b32 s44, v254, 16
	v_readlane_b32 s45, v254, 17
	v_readlane_b32 s46, v254, 18
	v_readlane_b32 s47, v254, 19
	v_readlane_b32 s48, v254, 20
	v_readlane_b32 s49, v254, 21
	v_readlane_b32 s50, v254, 22
	v_readlane_b32 s51, v254, 23
	s_waitcnt vmcnt(0)
	v_pk_add_f32 v[80:81], v[80:81], v[244:245] op_sel_hi:[1,0]
	v_pk_add_f32 v[82:83], v[82:83], v[244:245] op_sel_hi:[1,0]
	v_pk_add_f32 v[84:85], v[84:85], v[244:245] op_sel_hi:[1,0]
	v_pk_add_f32 v[86:87], v[86:87], v[244:245] op_sel_hi:[1,0]
	v_pk_add_f32 v[220:221], v[88:89], v[244:245] op_sel_hi:[1,0]
	v_pk_add_f32 v[222:223], v[90:91], v[244:245] op_sel_hi:[1,0]
	v_pk_add_f32 v[224:225], v[92:93], v[244:245] op_sel_hi:[1,0]
	v_pk_add_f32 v[226:227], v[94:95], v[244:245] op_sel_hi:[1,0]
	v_pk_mul_f32 v[94:95], v[80:81], v[204:205]
	v_pk_mul_f32 v[92:93], v[82:83], v[186:187]
	v_pk_mul_f32 v[90:91], v[84:85], v[206:207]
	v_pk_mul_f32 v[88:89], v[86:87], v[188:189]
	v_pk_add_f32 v[66:67], v[66:67], v[244:245] op_sel_hi:[1,0]
	v_pk_add_f32 v[70:71], v[70:71], v[244:245] op_sel_hi:[1,0]
	v_pk_mul_f32 v[86:87], v[220:221], v[208:209]
	v_pk_mul_f32 v[84:85], v[222:223], v[190:191]
	v_pk_mul_f32 v[80:81], v[226:227], v[192:193]
	v_pk_mul_f32 v[186:187], v[94:95], v[94:95]
	v_pk_mul_f32 v[188:189], v[92:93], v[92:93]
	v_pk_mul_f32 v[190:191], v[90:91], v[90:91]
	v_pk_mul_f32 v[192:193], v[88:89], v[88:89]
	v_pk_add_f32 v[230:231], v[74:75], v[244:245] op_sel_hi:[1,0]
	v_pk_mul_f32 v[74:75], v[66:67], v[194:195]
	v_pk_mul_f32 v[70:71], v[70:71], v[196:197]
	v_pk_mul_f32 v[194:195], v[86:87], v[86:87]
	v_pk_mul_f32 v[196:197], v[84:85], v[84:85]
	v_add_f32_e32 v192, v192, v193
	v_add_f32_e32 v190, v190, v191
	v_add_f32_e32 v188, v188, v189
	v_add_f32_e32 v186, v186, v187
	v_pk_mul_f32 v[82:83], v[224:225], v[210:211]
	v_add_f32_e32 v190, v190, v192
	v_add_f32_e32 v186, v186, v188
	v_add_f32_e32 v187, v196, v197
	v_add_f32_e32 v188, v194, v195
	v_pk_add_f32 v[64:65], v[64:65], v[244:245] op_sel_hi:[1,0]
	v_pk_mul_f32 v[66:67], v[230:231], v[198:199]
	v_pk_mul_f32 v[198:199], v[82:83], v[82:83]
	v_pk_mul_f32 v[204:205], v[80:81], v[80:81]
	v_add_f32_e32 v186, v186, v190
	v_add_f32_e32 v187, v188, v187
	v_pk_add_f32 v[232:233], v[76:77], v[244:245] op_sel_hi:[1,0]
	v_pk_mul_f32 v[76:77], v[64:65], v[212:213]
	v_add_f32_e32 v186, v186, v187
	v_add_f32_e32 v187, v204, v205
	v_add_f32_e32 v188, v198, v199
	v_pk_add_f32 v[68:69], v[68:69], v[244:245] op_sel_hi:[1,0]
	v_pk_mul_f32 v[206:207], v[76:77], v[76:77]
	v_pk_mul_f32 v[208:209], v[74:75], v[74:75]
	v_add_f32_e32 v187, v188, v187
	v_pk_add_f32 v[228:229], v[72:73], v[244:245] op_sel_hi:[1,0]
	v_pk_mul_f32 v[72:73], v[68:69], v[214:215]
	v_add_f32_e32 v186, v186, v187
	v_add_f32_e32 v187, v208, v209
	v_add_f32_e32 v188, v206, v207
	v_pk_mul_f32 v[210:211], v[72:73], v[72:73]
	v_pk_mul_f32 v[212:213], v[70:71], v[70:71]
	v_add_f32_e32 v187, v188, v187
	v_pk_mul_f32 v[68:69], v[228:229], v[216:217]
	v_add_f32_e32 v186, v186, v187
	v_add_f32_e32 v187, v212, v213
	v_add_f32_e32 v188, v210, v211
	v_pk_mul_f32 v[214:215], v[68:69], v[68:69]
	v_pk_mul_f32 v[216:217], v[66:67], v[66:67]
	v_pk_add_f32 v[78:79], v[78:79], v[244:245] op_sel_hi:[1,0]
	v_add_f32_e32 v187, v188, v187
	v_pk_mul_f32 v[64:65], v[232:233], v[218:219]
	v_pk_mul_f32 v[78:79], v[78:79], v[200:201]
	v_add_f32_e32 v186, v186, v187
	v_add_f32_e32 v187, v216, v217
	v_add_f32_e32 v188, v214, v215
	v_pk_mul_f32 v[200:201], v[64:65], v[64:65]
	v_pk_mul_f32 v[202:203], v[78:79], v[78:79]
	v_add_f32_e32 v187, v188, v187
	v_add_f32_e32 v186, v186, v187
	v_add_f32_e32 v187, v202, v203
	v_add_f32_e32 v188, v200, v201
	v_add_f32_e32 v187, v188, v187
	v_add_f32_e32 v186, v186, v187
	ds_bpermute_b32 v188, v182, v186
	v_or_b32_e32 v187, 32, v181
	s_and_saveexec_b64 s[12:13], vcc
	s_cbranch_execz .LBB0_882
	v_or_b32_e32 v189, s15, v187
	s_waitcnt lgkmcnt(0)
	v_add_f32_e32 v186, v186, v188
	v_lshl_add_u32 v188, v189, 2, 0
	v_add_u32_e32 v188, 0x22000, v188
	ds_write_b32 v188, v186
; #define LAS __attribute__((address_space(3)))
; __device__ __forceinline__ void phase4_gmlp(const Args& a, LAS unsigned char* lds) {
;     ...
;         for (int tt = 0; tt < 4; ++tt) {
;             const int tl = 32 * tt + r;
;             const float bias = sp_b[g * 128 + tl];
;             float ss = 0.f;
; #pragma unroll
;             for (int dt = 0; dt < 2; ++dt)
; #pragma unroll
;                 for (int ap = 0; ap < 4; ++ap) {
;                     const u32x2 zz = *(const LAS u32x2*)(tile + tl * G_TSTR + (32 * dt + 8 * ap + 4 * h) * 2);
;                     const float z0 = __uint_as_float(zz.x << 16), z1 = __uint_as_float(zz.x & 0xffff0000u), z2 = __uint_as_float(zz.y << 16), z3 = __uint_as_float(zz.y & 0xffff0000u);
;                     float v0 = z0 * (acc[dt][tt][4 * ap] + bias), v1 = z1 * (acc[dt][tt][4 * ap + 1] + bias), v2 = z2 * (acc[dt][tt][4 * ap + 2] + bias), v3 = z3 * (acc[dt][tt][4 * ap + 3] + bias);
;                     acc[dt][tt][4 * ap] = v0; acc[dt][tt][4 * ap + 1] = v1; acc[dt][tt][4 * ap + 2] = v2; acc[dt][tt][4 * ap + 3] = v3;
;                     ss += (v0 * v0 + v1 * v1) + (v2 * v2 + v3 * v3);
;                 }
;             ss += __shfl_xor(ss, 32);
;             if (h == 0) SSQ2[g * 128 + tl] = ss;
.LBB0_882:
	s_or_b64 exec, exec, s[12:13]
	v_add_u32_e32 v186, 0x2000, v185
	s_waitcnt lgkmcnt(0)
	ds_read2_b64 v[188:191], v186 offset0:64 offset1:66
	ds_read2_b64 v[192:195], v186 offset0:68 offset1:70
	ds_read2_b64 v[196:199], v186 offset0:72 offset1:74
	ds_read2_b64 v[200:203], v186 offset0:76 offset1:78
	s_waitcnt lgkmcnt(3)
	v_lshlrev_b32_e32 v206, 16, v188
	v_and_b32_e32 v207, 0xffff0000, v188
	v_lshlrev_b32_e32 v188, 16, v189
	v_and_b32_e32 v189, 0xffff0000, v189
	v_lshlrev_b32_e32 v208, 16, v190
	v_and_b32_e32 v209, 0xffff0000, v190
	v_lshlrev_b32_e32 v190, 16, v191
	v_and_b32_e32 v191, 0xffff0000, v191
	s_waitcnt lgkmcnt(2)
	v_lshlrev_b32_e32 v210, 16, v192
	v_and_b32_e32 v211, 0xffff0000, v192
	v_lshlrev_b32_e32 v192, 16, v193
	v_and_b32_e32 v193, 0xffff0000, v193
	v_lshlrev_b32_e32 v212, 16, v194
	v_and_b32_e32 v213, 0xffff0000, v194
	v_lshlrev_b32_e32 v194, 16, v195
	v_and_b32_e32 v195, 0xffff0000, v195
	s_waitcnt lgkmcnt(1)
	v_lshlrev_b32_e32 v214, 16, v196
	v_and_b32_e32 v215, 0xffff0000, v196
	v_lshlrev_b32_e32 v196, 16, v197
	v_and_b32_e32 v197, 0xffff0000, v197
	v_lshlrev_b32_e32 v216, 16, v198
	v_and_b32_e32 v217, 0xffff0000, v198
	v_lshlrev_b32_e32 v198, 16, v199
	v_and_b32_e32 v199, 0xffff0000, v199
	s_waitcnt lgkmcnt(0)
	v_lshlrev_b32_e32 v218, 16, v200
	v_and_b32_e32 v219, 0xffff0000, v200
	v_lshlrev_b32_e32 v200, 16, v201
	v_and_b32_e32 v201, 0xffff0000, v201
	v_lshlrev_b32_e32 v220, 16, v202
	v_and_b32_e32 v221, 0xffff0000, v202
	v_lshlrev_b32_e32 v202, 16, v203
	v_and_b32_e32 v203, 0xffff0000, v203
	s_waitcnt vmcnt(0)
	v_pk_add_f32 v[48:49], v[48:49], v[246:247] op_sel_hi:[1,0]
	v_pk_add_f32 v[50:51], v[50:51], v[246:247] op_sel_hi:[1,0]
	v_pk_add_f32 v[52:53], v[52:53], v[246:247] op_sel_hi:[1,0]
	v_pk_add_f32 v[54:55], v[54:55], v[246:247] op_sel_hi:[1,0]
	v_pk_add_f32 v[222:223], v[56:57], v[246:247] op_sel_hi:[1,0]
	v_pk_add_f32 v[224:225], v[58:59], v[246:247] op_sel_hi:[1,0]
	v_pk_add_f32 v[226:227], v[60:61], v[246:247] op_sel_hi:[1,0]
	v_pk_add_f32 v[228:229], v[62:63], v[246:247] op_sel_hi:[1,0]
	v_pk_mul_f32 v[62:63], v[48:49], v[206:207]
	v_pk_mul_f32 v[60:61], v[50:51], v[188:189]
	v_pk_mul_f32 v[58:59], v[52:53], v[208:209]
	v_pk_mul_f32 v[56:57], v[54:55], v[190:191]
	v_pk_add_f32 v[34:35], v[34:35], v[246:247] op_sel_hi:[1,0]
	v_pk_add_f32 v[38:39], v[38:39], v[246:247] op_sel_hi:[1,0]
	v_pk_mul_f32 v[54:55], v[222:223], v[210:211]
	v_pk_mul_f32 v[52:53], v[224:225], v[192:193]
	v_pk_mul_f32 v[48:49], v[228:229], v[194:195]
	v_pk_mul_f32 v[188:189], v[62:63], v[62:63]
	v_pk_mul_f32 v[190:191], v[60:61], v[60:61]
	v_pk_mul_f32 v[192:193], v[58:59], v[58:59]
	v_pk_mul_f32 v[194:195], v[56:57], v[56:57]
	v_pk_add_f32 v[232:233], v[42:43], v[246:247] op_sel_hi:[1,0]
	v_pk_mul_f32 v[42:43], v[34:35], v[196:197]
	v_pk_mul_f32 v[38:39], v[38:39], v[198:199]
	v_pk_mul_f32 v[196:197], v[54:55], v[54:55]
	v_pk_mul_f32 v[198:199], v[52:53], v[52:53]
	v_add_f32_e32 v194, v194, v195
	v_add_f32_e32 v192, v192, v193
	v_add_f32_e32 v190, v190, v191
	v_add_f32_e32 v188, v188, v189
	v_pk_mul_f32 v[50:51], v[226:227], v[212:213]
	v_add_f32_e32 v192, v192, v194
	v_add_f32_e32 v188, v188, v190
	v_add_f32_e32 v189, v198, v199
	v_add_f32_e32 v190, v196, v197
	v_pk_add_f32 v[32:33], v[32:33], v[246:247] op_sel_hi:[1,0]
	v_pk_add_f32 v[36:37], v[36:37], v[246:247] op_sel_hi:[1,0]
	v_pk_add_f32 v[230:231], v[40:41], v[246:247] op_sel_hi:[1,0]
	v_pk_add_f32 v[234:235], v[44:45], v[246:247] op_sel_hi:[1,0]
	v_pk_add_f32 v[46:47], v[46:47], v[246:247] op_sel_hi:[1,0]
	v_pk_mul_f32 v[34:35], v[232:233], v[200:201]
	v_pk_mul_f32 v[200:201], v[50:51], v[50:51]
	v_pk_mul_f32 v[204:205], v[48:49], v[48:49]
	v_add_f32_e32 v188, v188, v192
	v_add_f32_e32 v189, v190, v189
	v_pk_mul_f32 v[44:45], v[32:33], v[214:215]
	v_add_f32_e32 v188, v188, v189
	v_add_f32_e32 v189, v204, v205
	v_add_f32_e32 v190, v200, v201
	v_pk_mul_f32 v[206:207], v[44:45], v[44:45]
	v_pk_mul_f32 v[208:209], v[42:43], v[42:43]
	v_add_f32_e32 v189, v190, v189
	v_pk_mul_f32 v[40:41], v[36:37], v[216:217]
	v_add_f32_e32 v188, v188, v189
	v_add_f32_e32 v189, v208, v209
	v_add_f32_e32 v190, v206, v207
	v_pk_mul_f32 v[210:211], v[40:41], v[40:41]
	v_pk_mul_f32 v[212:213], v[38:39], v[38:39]
	v_add_f32_e32 v189, v190, v189
	v_pk_mul_f32 v[36:37], v[230:231], v[218:219]
	v_add_f32_e32 v188, v188, v189
	v_add_f32_e32 v189, v212, v213
	v_add_f32_e32 v190, v210, v211
	v_pk_mul_f32 v[214:215], v[36:37], v[36:37]
	v_pk_mul_f32 v[216:217], v[34:35], v[34:35]
	v_add_f32_e32 v189, v190, v189
	v_pk_mul_f32 v[32:33], v[234:235], v[220:221]
	v_pk_mul_f32 v[46:47], v[46:47], v[202:203]
	v_add_f32_e32 v188, v188, v189
	v_add_f32_e32 v189, v216, v217
	v_add_f32_e32 v190, v214, v215
	v_pk_mul_f32 v[202:203], v[32:33], v[32:33]
	v_pk_mul_f32 v[218:219], v[46:47], v[46:47]
	v_add_f32_e32 v189, v190, v189
	v_add_f32_e32 v188, v188, v189
	v_add_f32_e32 v189, v218, v219
	v_add_f32_e32 v190, v202, v203
	v_add_f32_e32 v189, v190, v189
	v_add_f32_e32 v189, v188, v189
	ds_bpermute_b32 v190, v182, v189
	v_or_b32_e32 v188, 64, v181
	s_and_saveexec_b64 s[12:13], vcc
	s_cbranch_execz .LBB0_884
	v_or_b32_e32 v191, s15, v188
	s_waitcnt lgkmcnt(0)
	v_add_f32_e32 v189, v189, v190
	v_lshl_add_u32 v190, v191, 2, 0
	v_add_u32_e32 v190, 0x22000, v190
	ds_write_b32 v190, v189
; #define LAS __attribute__((address_space(3)))
; __device__ __forceinline__ void phase4_gmlp(const Args& a, LAS unsigned char* lds) {
;     ...
;         for (int tt = 0; tt < 4; ++tt) {
;             const int tl = 32 * tt + r;
;             const float bias = sp_b[g * 128 + tl];
;             float ss = 0.f;
; #pragma unroll
;             for (int dt = 0; dt < 2; ++dt)
; #pragma unroll
;                 for (int ap = 0; ap < 4; ++ap) {
;                     const u32x2 zz = *(const LAS u32x2*)(tile + tl * G_TSTR + (32 * dt + 8 * ap + 4 * h) * 2);
;                     const float z0 = __uint_as_float(zz.x << 16), z1 = __uint_as_float(zz.x & 0xffff0000u), z2 = __uint_as_float(zz.y << 16), z3 = __uint_as_float(zz.y & 0xffff0000u);
;                     float v0 = z0 * (acc[dt][tt][4 * ap] + bias), v1 = z1 * (acc[dt][tt][4 * ap + 1] + bias), v2 = z2 * (acc[dt][tt][4 * ap + 2] + bias), v3 = z3 * (acc[dt][tt][4 * ap + 3] + bias);
;                     acc[dt][tt][4 * ap] = v0; acc[dt][tt][4 * ap + 1] = v1; acc[dt][tt][4 * ap + 2] = v2; acc[dt][tt][4 * ap + 3] = v3;
;                     ss += (v0 * v0 + v1 * v1) + (v2 * v2 + v3 * v3);
;                 }
;             ss += __shfl_xor(ss, 32);
;             if (h == 0) SSQ2[g * 128 + tl] = ss;
;         }
.LBB0_884:
	s_or_b64 exec, exec, s[12:13]
	v_add_u32_e32 v162, 0x3000, v185
	s_waitcnt lgkmcnt(0)
	ds_read2_b64 v[190:193], v162 offset0:96 offset1:98
	ds_read2_b64 v[194:197], v162 offset0:100 offset1:102
	ds_read2_b64 v[198:201], v162 offset0:104 offset1:106
	ds_read2_b64 v[202:205], v162 offset0:108 offset1:110
	s_waitcnt lgkmcnt(3)
	v_lshlrev_b32_e32 v210, 16, v192
	v_and_b32_e32 v211, 0xffff0000, v192
	v_lshlrev_b32_e32 v192, 16, v193
	v_and_b32_e32 v193, 0xffff0000, v193
	v_lshlrev_b32_e32 v208, 16, v190
	v_and_b32_e32 v209, 0xffff0000, v190
	v_lshlrev_b32_e32 v190, 16, v191
	v_and_b32_e32 v191, 0xffff0000, v191
	s_waitcnt lgkmcnt(2)
	v_lshlrev_b32_e32 v212, 16, v194
	v_and_b32_e32 v213, 0xffff0000, v194
	v_lshlrev_b32_e32 v194, 16, v195
	v_and_b32_e32 v195, 0xffff0000, v195
	v_lshlrev_b32_e32 v214, 16, v196
	v_and_b32_e32 v215, 0xffff0000, v196
	v_lshlrev_b32_e32 v196, 16, v197
	v_and_b32_e32 v197, 0xffff0000, v197
	s_waitcnt lgkmcnt(1)
	v_lshlrev_b32_e32 v216, 16, v198
	v_and_b32_e32 v217, 0xffff0000, v198
	v_lshlrev_b32_e32 v198, 16, v199
	v_and_b32_e32 v199, 0xffff0000, v199
	v_lshlrev_b32_e32 v218, 16, v200
	v_and_b32_e32 v219, 0xffff0000, v200
	v_lshlrev_b32_e32 v200, 16, v201
	v_and_b32_e32 v201, 0xffff0000, v201
	s_waitcnt lgkmcnt(0)
	v_lshlrev_b32_e32 v220, 16, v202
	v_and_b32_e32 v221, 0xffff0000, v202
	v_lshlrev_b32_e32 v202, 16, v203
	v_and_b32_e32 v203, 0xffff0000, v203
	v_lshlrev_b32_e32 v222, 16, v204
	v_and_b32_e32 v223, 0xffff0000, v204
	v_lshlrev_b32_e32 v204, 16, v205
	v_and_b32_e32 v205, 0xffff0000, v205
	s_waitcnt vmcnt(0)
	v_pk_add_f32 v[20:21], v[20:21], v[248:249] op_sel_hi:[1,0]
	v_pk_add_f32 v[22:23], v[22:23], v[248:249] op_sel_hi:[1,0]
	v_pk_add_f32 v[16:17], v[16:17], v[248:249] op_sel_hi:[1,0]
	v_pk_add_f32 v[18:19], v[18:19], v[248:249] op_sel_hi:[1,0]
	v_pk_add_f32 v[224:225], v[24:25], v[248:249] op_sel_hi:[1,0]
	v_pk_add_f32 v[226:227], v[26:27], v[248:249] op_sel_hi:[1,0]
	v_pk_add_f32 v[230:231], v[30:31], v[248:249] op_sel_hi:[1,0]
	v_pk_mul_f32 v[26:27], v[20:21], v[210:211]
	v_pk_mul_f32 v[24:25], v[22:23], v[192:193]
	v_pk_add_f32 v[228:229], v[28:29], v[248:249] op_sel_hi:[1,0]
	v_pk_mul_f32 v[30:31], v[16:17], v[208:209]
	v_pk_mul_f32 v[28:29], v[18:19], v[190:191]
	v_pk_mul_f32 v[20:21], v[226:227], v[194:195]
	v_pk_mul_f32 v[16:17], v[230:231], v[196:197]
	v_pk_mul_f32 v[194:195], v[26:27], v[26:27]
	v_pk_mul_f32 v[196:197], v[24:25], v[24:25]
	v_pk_mul_f32 v[190:191], v[30:31], v[30:31]
	v_pk_mul_f32 v[192:193], v[28:29], v[28:29]
	v_add_f32_e32 v163, v196, v197
	v_add_f32_e32 v189, v194, v195
	v_pk_add_f32 v[2:3], v[2:3], v[248:249] op_sel_hi:[1,0]
	v_pk_add_f32 v[6:7], v[6:7], v[248:249] op_sel_hi:[1,0]
	v_pk_mul_f32 v[22:23], v[224:225], v[212:213]
	v_add_f32_e32 v163, v189, v163
	v_add_f32_e32 v189, v192, v193
	v_add_f32_e32 v190, v190, v191
	v_pk_add_f32 v[234:235], v[10:11], v[248:249] op_sel_hi:[1,0]
	v_pk_mul_f32 v[10:11], v[2:3], v[198:199]
	v_pk_mul_f32 v[6:7], v[6:7], v[200:201]
	v_pk_mul_f32 v[198:199], v[22:23], v[22:23]
	v_pk_mul_f32 v[200:201], v[20:21], v[20:21]
	v_add_f32_e32 v189, v190, v189
	v_pk_mul_f32 v[18:19], v[228:229], v[214:215]
	v_add_f32_e32 v163, v189, v163
	v_add_f32_e32 v189, v200, v201
	v_add_f32_e32 v190, v198, v199
	v_pk_add_f32 v[0:1], v[0:1], v[248:249] op_sel_hi:[1,0]
	v_pk_add_f32 v[4:5], v[4:5], v[248:249] op_sel_hi:[1,0]
	v_pk_add_f32 v[232:233], v[8:9], v[248:249] op_sel_hi:[1,0]
	v_pk_add_f32 v[236:237], v[12:13], v[248:249] op_sel_hi:[1,0]
	v_pk_add_f32 v[14:15], v[14:15], v[248:249] op_sel_hi:[1,0]
	v_pk_mul_f32 v[2:3], v[234:235], v[202:203]
	v_pk_mul_f32 v[202:203], v[18:19], v[18:19]
	v_pk_mul_f32 v[206:207], v[16:17], v[16:17]
	v_add_f32_e32 v189, v190, v189
	v_pk_mul_f32 v[12:13], v[0:1], v[216:217]
	v_add_f32_e32 v163, v163, v189
	v_add_f32_e32 v189, v206, v207
	v_add_f32_e32 v190, v202, v203
	v_pk_mul_f32 v[208:209], v[12:13], v[12:13]
	v_pk_mul_f32 v[210:211], v[10:11], v[10:11]
	v_add_f32_e32 v189, v190, v189
	v_pk_mul_f32 v[8:9], v[4:5], v[218:219]
	v_add_f32_e32 v163, v163, v189
	v_add_f32_e32 v189, v210, v211
	v_add_f32_e32 v190, v208, v209
	v_pk_mul_f32 v[212:213], v[8:9], v[8:9]
	v_pk_mul_f32 v[214:215], v[6:7], v[6:7]
	v_add_f32_e32 v189, v190, v189
	v_pk_mul_f32 v[4:5], v[232:233], v[220:221]
	v_add_f32_e32 v163, v163, v189
	v_add_f32_e32 v189, v214, v215
	v_add_f32_e32 v190, v212, v213
	v_pk_mul_f32 v[216:217], v[4:5], v[4:5]
	v_pk_mul_f32 v[218:219], v[2:3], v[2:3]
	v_add_f32_e32 v189, v190, v189
	v_pk_mul_f32 v[0:1], v[236:237], v[222:223]
	v_pk_mul_f32 v[14:15], v[14:15], v[204:205]
	v_add_f32_e32 v163, v163, v189
	v_add_f32_e32 v189, v218, v219
	v_add_f32_e32 v190, v216, v217
	v_pk_mul_f32 v[204:205], v[0:1], v[0:1]
	v_pk_mul_f32 v[220:221], v[14:15], v[14:15]
	v_add_f32_e32 v189, v190, v189
	v_add_f32_e32 v163, v163, v189
	v_add_f32_e32 v189, v220, v221
	v_add_f32_e32 v190, v204, v205
	v_add_f32_e32 v189, v190, v189
	v_add_f32_e32 v189, v163, v189
	ds_bpermute_b32 v182, v182, v189
	v_or_b32_e32 v163, 0x60, v181
	s_and_saveexec_b64 s[12:13], vcc
	s_cbranch_execz .LBB0_877
	v_or_b32_e32 v190, s15, v163
	s_waitcnt lgkmcnt(0)
	v_add_f32_e32 v182, v189, v182
	v_lshl_add_u32 v189, v190, 2, 0
	v_add_u32_e32 v189, 0x22000, v189
	ds_write_b32 v189, v182
	s_branch .LBB0_877
